# store widening: dilated per-slab f32 output tile stored as 4 dwordx4 after an in-quad 4x4 DPP transpose (was 16 dword stores); chunk: scale load and first C0 slice staging loads hoisted
# speedup vs baseline: 1.0060x; 1.0060x over previous
.LBB0_1244:
	s_or_b64 exec, exec, s[20:21]
	s_ashr_i32 s20, s16, 9
	s_and_b32 s60, s16, 0x7f
	s_ashr_i32 s21, s20, 31
	s_lshl_b64 s[20:21], s[20:21], 14
	s_lshl_b32 s17, s60, 7
	s_or_b32 s38, s20, s17
	s_lshl_b32 s14, s65, 1
	v_readlane_b32 s40, v253, 2
	s_add_u32 s58, s40, s14
	v_readlane_b32 s14, v252, 5
	s_addc_u32 s59, s14, 0
	s_mov_b32 s39, s21
	s_mov_b64 s[56:57], 0
	v_mov_b64_e32 v[2:3], s[58:59]
	v_mov_b32_e32 v40, v176
	s_cmp_gt_u32 s60, 63
	s_cselect_b32 s99, s68, s16
	v_readlane_b32 vcc_lo, v252, 16
	v_readlane_b32 vcc_hi, v252, 17
	s_cbranch_scc1 .Lc0_first_a
	v_readlane_b32 vcc_lo, v252, 6
	v_readlane_b32 vcc_hi, v252, 7
.Lc0_first_a:
	s_mul_hi_i32 s98, s99, 0x13800
	s_mul_i32 s99, s99, 0x13800
	s_nop 3
	s_add_u32 vcc_lo, vcc_lo, s99
	s_addc_u32 vcc_hi, vcc_hi, s98
	s_nop 3
	v_lshl_add_u64 v[248:249], vcc, 0, v[86:87]
	global_load_dwordx4 v[232:235], v[248:249], off
	v_add_co_u32_e32 v248, vcc, 0x6000, v248
	s_nop 1
	v_addc_co_u32_e32 v249, vcc, 0, v249, vcc
	global_load_dwordx4 v[236:239], v[248:249], off
	v_add_co_u32_e32 v248, vcc, 0x6000, v248
	s_nop 1
	v_addc_co_u32_e32 v249, vcc, 0, v249, vcc
	global_load_dwordx4 v[240:243], v[248:249], off
	v_add_co_u32_e32 v248, vcc, 0x6000, v248
	s_nop 1
	v_addc_co_u32_e32 v249, vcc, 0, v249, vcc
	v_cmp_gt_u32_e32 vcc, 0x80, v176
	s_and_saveexec_b64 s[98:99], vcc
	global_load_dwordx4 v[244:247], v[248:249], off
	s_or_b64 exec, exec, s[98:99]
	s_mov_b32 s98, 1
	s_branch .LBB0_1246

.LBB0_1266:
	s_or_b64 exec, exec, s[56:57]
	ds_read_b32 v0, v75 offset:51648
	s_cmp_gt_u32 s60, 63
	s_cselect_b64 s[38:39], -1, 0
	s_and_b64 s[56:57], s[38:39], exec
	s_mul_i32 s14, s16, 0x13800
	s_waitcnt lgkmcnt(0)
	v_sub_f32_e32 v2, v0, v8
	v_mul_f32_e32 v2, 0x3fb8aa3b, v2
	v_exp_f32_e32 v2, v2
	v_sub_f32_e32 v3, v0, v9
	v_mul_f32_e32 v3, 0x3fb8aa3b, v3
	v_exp_f32_e32 v3, v3
	v_mul_f32_e32 v2, v36, v2
	v_cndmask_b32_e64 v2, v2, 0, s[70:71]
	v_sub_f32_e32 v8, v0, v10
	v_bfe_u32 v9, v2, 16, 1
	v_mul_f32_e32 v8, 0x3fb8aa3b, v8
	v_add3_u32 v2, v2, v9, s64
	ds_write_b16_d16_hi v104, v2 offset:56032
	v_exp_f32_e32 v2, v8
	v_sub_f32_e32 v0, v0, v11
	v_mul_f32_e32 v0, 0x3fb8aa3b, v0
	v_mul_f32_e32 v3, v37, v3
	v_exp_f32_e32 v0, v0
	v_cndmask_b32_e64 v3, v3, 0, s[72:73]
	v_bfe_u32 v8, v3, 16, 1
	v_mul_f32_e32 v2, v38, v2
	v_add3_u32 v3, v3, v8, s64
	v_cndmask_b32_e64 v2, v2, 0, s[80:81]
	v_readlane_b32 s40, v252, 6
	ds_write_b16_d16_hi v104, v3 offset:56304
	v_bfe_u32 v3, v2, 16, 1
	v_mul_f32_e32 v0, v39, v0
	s_cselect_b32 s61, 0, 3
	s_mul_hi_i32 s56, s16, 0x13800
	s_add_u32 s14, s40, s14
	v_readlane_b32 s40, v252, 7
	v_add3_u32 v2, v2, v3, s64
	v_cndmask_b32_e64 v0, v0, 0, s[82:83]
	s_addc_u32 s58, s40, s56
	s_mul_hi_i32 s56, s68, 0x13800
	s_mul_i32 s68, s68, 0x13800
	v_readlane_b32 s40, v252, 16
	ds_write_b16_d16_hi v104, v2 offset:56576
	v_bfe_u32 v2, v0, 16, 1
	s_add_u32 s59, s40, s68
	v_readlane_b32 s40, v252, 17
	v_add3_u32 v0, v0, v2, s64
	s_addc_u32 s60, s40, s56
	v_readlane_b32 s40, v252, 14
	v_mov_b32_e32 v2, v1
	v_mov_b32_e32 v3, v1
	ds_write_b16_d16_hi v104, v0 offset:56848
	s_add_u32 s18, s40, s18
	v_readlane_b32 s40, v252, 15
	v_mov_b32_e32 v0, v1
	v_mov_b64_e32 v[54:55], v[2:3]
	v_mov_b64_e32 v[50:51], v[2:3]
	v_mov_b64_e32 v[46:47], v[2:3]
	v_mov_b64_e32 v[42:43], v[2:3]
	v_mov_b64_e32 v[38:39], v[2:3]
	v_mov_b64_e32 v[34:35], v[2:3]
	v_mov_b64_e32 v[30:31], v[2:3]
	v_mov_b64_e32 v[26:27], v[2:3]
	v_mov_b64_e32 v[22:23], v[2:3]
	v_mov_b64_e32 v[18:19], v[2:3]
	v_mov_b64_e32 v[14:15], v[2:3]
	v_mov_b64_e32 v[10:11], v[2:3]
	v_mov_b64_e32 v[58:59], v[2:3]
	s_addc_u32 s19, s40, s19
	v_mov_b64_e32 v[52:53], v[0:1]
	v_mov_b64_e32 v[48:49], v[0:1]
	v_mov_b64_e32 v[44:45], v[0:1]
	v_mov_b64_e32 v[40:41], v[0:1]
	v_mov_b64_e32 v[36:37], v[0:1]
	v_mov_b64_e32 v[32:33], v[0:1]
	v_mov_b64_e32 v[28:29], v[0:1]
	v_mov_b64_e32 v[24:25], v[0:1]
	v_mov_b64_e32 v[20:21], v[0:1]
	v_mov_b64_e32 v[16:17], v[0:1]
	v_mov_b64_e32 v[12:13], v[0:1]
	v_mov_b64_e32 v[8:9], v[0:1]
	v_mov_b64_e32 v[56:57], v[0:1]
	s_and_b64 vcc, exec, s[38:39]
	s_cbranch_vccz .Lc0_noscl
	v_mov_b64_e32 v[250:251], s[18:19]
	global_load_dword v250, v[250:251], off
.Lc0_noscl:
.LBB0_1267:
	s_cmp_eq_u32 s61, 3
	s_cselect_b64 s[56:57], -1, 0
	s_and_b64 s[56:57], s[56:57], s[38:39]
	s_andn2_b64 vcc, exec, s[56:57]
	s_cbranch_vccnz .LBB0_1269
	s_waitcnt vmcnt(0)
	v_mov_b32_e32 v0, v250
	v_pk_mul_f32 v[10:11], v[10:11], v[0:1] op_sel_hi:[1,0]
	v_pk_mul_f32 v[8:9], v[8:9], v[0:1] op_sel_hi:[1,0]
	v_pk_mul_f32 v[14:15], v[14:15], v[0:1] op_sel_hi:[1,0]
	v_pk_mul_f32 v[12:13], v[12:13], v[0:1] op_sel_hi:[1,0]
	v_pk_mul_f32 v[18:19], v[18:19], v[0:1] op_sel_hi:[1,0]
	v_pk_mul_f32 v[16:17], v[16:17], v[0:1] op_sel_hi:[1,0]
	v_pk_mul_f32 v[22:23], v[22:23], v[0:1] op_sel_hi:[1,0]
	v_pk_mul_f32 v[20:21], v[20:21], v[0:1] op_sel_hi:[1,0]
	v_pk_mul_f32 v[26:27], v[26:27], v[0:1] op_sel_hi:[1,0]
	v_pk_mul_f32 v[24:25], v[24:25], v[0:1] op_sel_hi:[1,0]
	v_pk_mul_f32 v[30:31], v[30:31], v[0:1] op_sel_hi:[1,0]
	v_pk_mul_f32 v[28:29], v[28:29], v[0:1] op_sel_hi:[1,0]
	v_pk_mul_f32 v[34:35], v[34:35], v[0:1] op_sel_hi:[1,0]
	v_pk_mul_f32 v[32:33], v[32:33], v[0:1] op_sel_hi:[1,0]
	v_pk_mul_f32 v[38:39], v[38:39], v[0:1] op_sel_hi:[1,0]
	v_pk_mul_f32 v[36:37], v[36:37], v[0:1] op_sel_hi:[1,0]
	v_pk_mul_f32 v[42:43], v[42:43], v[0:1] op_sel_hi:[1,0]
	v_pk_mul_f32 v[40:41], v[40:41], v[0:1] op_sel_hi:[1,0]
	v_pk_mul_f32 v[46:47], v[46:47], v[0:1] op_sel_hi:[1,0]
	v_pk_mul_f32 v[44:45], v[44:45], v[0:1] op_sel_hi:[1,0]
	v_pk_mul_f32 v[50:51], v[50:51], v[0:1] op_sel_hi:[1,0]
	v_pk_mul_f32 v[48:49], v[48:49], v[0:1] op_sel_hi:[1,0]
	v_pk_mul_f32 v[54:55], v[54:55], v[0:1] op_sel_hi:[1,0]
	v_pk_mul_f32 v[52:53], v[52:53], v[0:1] op_sel_hi:[1,0]
	v_pk_mul_f32 v[58:59], v[58:59], v[0:1] op_sel_hi:[1,0]
	v_pk_mul_f32 v[56:57], v[56:57], v[0:1] op_sel_hi:[1,0]

.LBB0_2084:
	s_mov_b64 s[52:53], -1
	v_bfe_u32 v48, v12, 16, 1
	v_add3_u32 v12, v12, v48, s70
	ds_write_b16_d16_hi v54, v12 offset:4688
	v_bfe_u32 v12, v16, 16, 1
	v_add3_u32 v12, v16, v12, s70
	ds_write_b16_d16_hi v54, v12 offset:4720
	v_bfe_u32 v12, v20, 16, 1
	v_add3_u32 v12, v20, v12, s70
	ds_write_b16_d16_hi v54, v12 offset:4752
	v_bfe_u32 v12, v24, 16, 1
	v_add3_u32 v12, v24, v12, s70
	ds_write_b16_d16_hi v54, v12 offset:4784
	v_bfe_u32 v12, v28, 16, 1
	v_add3_u32 v12, v28, v12, s70
	ds_write_b16_d16_hi v54, v12 offset:4816
	v_bfe_u32 v12, v32, 16, 1
	v_add3_u32 v12, v32, v12, s70
	ds_write_b16_d16_hi v54, v12 offset:4848
	v_bfe_u32 v12, v77, 16, 1
	v_add3_u32 v12, v77, v12, s70
	ds_write_b16_d16_hi v54, v12 offset:4880
	v_bfe_u32 v12, v78, 16, 1
	v_add3_u32 v12, v78, v12, s70
	ds_write_b16_d16_hi v54, v12 offset:4912
	v_bfe_u32 v12, v79, 16, 1
	v_add3_u32 v12, v79, v12, s70
	ds_write_b16 v54, v37 offset:4656
	ds_write_b16_d16_hi v54, v12 offset:4944
	ds_write_b16 v54, v37 offset:4992
	v_bfe_u32 v12, v1, 16, 1
	v_add3_u32 v1, v1, v12, s70
	ds_write_b16_d16_hi v54, v1 offset:5024
	v_bfe_u32 v1, v5, 16, 1
	v_add3_u32 v1, v5, v1, s70
	ds_write_b16_d16_hi v54, v1 offset:5056
	v_bfe_u32 v1, v13, 16, 1
	v_add3_u32 v1, v13, v1, s70
	ds_write_b16_d16_hi v54, v1 offset:5088
	v_bfe_u32 v1, v17, 16, 1
	v_add3_u32 v1, v17, v1, s70
	ds_write_b16_d16_hi v54, v1 offset:5120
	v_bfe_u32 v1, v21, 16, 1
	v_add3_u32 v1, v21, v1, s70
	ds_write_b16_d16_hi v54, v1 offset:5152
	v_bfe_u32 v1, v25, 16, 1
	v_add3_u32 v1, v25, v1, s70
	ds_write_b16_d16_hi v54, v1 offset:5184
	v_bfe_u32 v1, v29, 16, 1
	v_add3_u32 v1, v29, v1, s70
	ds_write_b16_d16_hi v54, v1 offset:5216
	v_bfe_u32 v1, v33, 16, 1
	v_add3_u32 v1, v33, v1, s70
	ds_write_b16_d16_hi v54, v1 offset:5248
	v_bfe_u32 v1, v36, 16, 1
	v_add3_u32 v1, v36, v1, s70
	ds_write_b16_d16_hi v54, v1 offset:5280
	ds_write_b16 v54, v37 offset:5328
	v_bfe_u32 v1, v14, 16, 1
	v_add3_u32 v1, v14, v1, s70
	ds_write_b16_d16_hi v54, v1 offset:5360
	v_bfe_u32 v1, v18, 16, 1
	v_add3_u32 v1, v18, v1, s70
	ds_write_b16_d16_hi v54, v1 offset:5392
	v_bfe_u32 v1, v22, 16, 1
	v_add3_u32 v1, v22, v1, s70
	ds_write_b16_d16_hi v54, v1 offset:5424
	v_bfe_u32 v1, v26, 16, 1
	v_add3_u32 v1, v26, v1, s70
	ds_write_b16_d16_hi v54, v1 offset:5456
	v_bfe_u32 v1, v30, 16, 1
	v_add3_u32 v1, v30, v1, s70
	ds_write_b16_d16_hi v54, v1 offset:5488
	v_bfe_u32 v1, v34, 16, 1
	v_add3_u32 v1, v34, v1, s70
	ds_write_b16_d16_hi v54, v1 offset:5520
	v_bfe_u32 v1, v89, 16, 1
	v_add3_u32 v1, v89, v1, s70
	ds_write_b16_d16_hi v54, v1 offset:5552
	v_bfe_u32 v1, v90, 16, 1
	v_add3_u32 v1, v90, v1, s70
	ds_write_b16_d16_hi v54, v1 offset:5584
	v_bfe_u32 v1, v91, 16, 1
	v_add3_u32 v1, v91, v1, s70
	ds_write_b16_d16_hi v54, v1 offset:5616
	ds_write_b16 v54, v37 offset:5664
	v_bfe_u32 v1, v3, 16, 1
	v_add3_u32 v1, v3, v1, s70
	ds_write_b16_d16_hi v54, v1 offset:5696
	v_bfe_u32 v1, v7, 16, 1
	v_add3_u32 v1, v7, v1, s70
	ds_write_b16_d16_hi v54, v1 offset:5728
	v_bfe_u32 v1, v15, 16, 1
	v_add3_u32 v1, v15, v1, s70
	ds_write_b16_d16_hi v54, v1 offset:5760
	v_bfe_u32 v1, v19, 16, 1
	v_add3_u32 v1, v19, v1, s70
	ds_write_b16_d16_hi v54, v1 offset:5792
	v_bfe_u32 v1, v23, 16, 1
	v_add3_u32 v1, v23, v1, s70
	ds_write_b16_d16_hi v54, v1 offset:5824
	v_bfe_u32 v1, v27, 16, 1
	v_add3_u32 v1, v27, v1, s70
	ds_write_b16_d16_hi v54, v1 offset:5856
	v_bfe_u32 v1, v31, 16, 1
	v_add3_u32 v1, v31, v1, s70
	ds_write_b16_d16_hi v54, v1 offset:5888
	v_bfe_u32 v1, v35, 16, 1
	v_add3_u32 v1, v35, v1, s70
	ds_write_b16_d16_hi v54, v1 offset:5920
	v_bfe_u32 v1, v49, 16, 1
	v_add3_u32 v1, v49, v1, s70
	ds_write_b16_d16_hi v54, v1 offset:5952
	ds_read_b128 v[100:103], v56 offset:4656
	ds_read_b128 v[104:107], v56 offset:4720
	ds_read_b128 v[108:111], v56 offset:4784
	ds_read_b128 v[112:115], v56 offset:4848
	ds_read_b128 v[116:119], v56 offset:4912
	s_waitcnt vmcnt(0) lgkmcnt(0)
	v_mfma_f32_16x16x32_bf16 v[12:15], v[100:103], v[120:123], 0
	v_mfma_f32_16x16x32_bf16 v[16:19], v[100:103], v[124:127], 0
	v_mfma_f32_16x16x32_bf16 v[28:31], v[100:103], v[128:131], 0
	v_mfma_f32_16x16x32_bf16 v[20:23], v[100:103], v[132:135], 0
	v_mfma_f32_16x16x32_bf16 v[12:15], v[104:107], v[136:139], v[12:15]
	v_mfma_f32_16x16x32_bf16 v[16:19], v[104:107], v[140:143], v[16:19]
	v_mfma_f32_16x16x32_bf16 v[28:31], v[104:107], v[144:147], v[28:31]
	v_mfma_f32_16x16x32_bf16 v[20:23], v[104:107], v[148:151], v[20:23]
	v_mfma_f32_16x16x32_bf16 v[12:15], v[108:111], v[152:155], v[12:15]
	v_mfma_f32_16x16x32_bf16 v[16:19], v[108:111], v[156:159], v[16:19]
	v_mfma_f32_16x16x32_bf16 v[28:31], v[108:111], v[160:163], v[28:31]
	v_mfma_f32_16x16x32_bf16 v[20:23], v[108:111], v[164:167], v[20:23]
	v_mfma_f32_16x16x32_bf16 v[12:15], v[112:115], v[168:171], v[12:15]
	v_mfma_f32_16x16x32_bf16 v[16:19], v[112:115], v[172:175], v[16:19]
	v_mfma_f32_16x16x32_bf16 v[28:31], v[112:115], v[180:183], v[28:31]
	v_mfma_f32_16x16x32_bf16 v[20:23], v[112:115], v[184:187], v[20:23]
	v_mfma_f32_16x16x32_bf16 v[12:15], v[116:119], v[188:191], v[12:15]
	v_mfma_f32_16x16x32_bf16 v[16:19], v[116:119], v[192:195], v[16:19]
	v_mfma_f32_16x16x32_bf16 v[28:31], v[116:119], v[196:199], v[28:31]
	v_mfma_f32_16x16x32_bf16 v[20:23], v[116:119], v[200:203], v[20:23]
	s_nop 7
	s_nop 1
	v_lshlrev_b32_e32 v1, 6, v74
	v_lshlrev_b32_e32 v36, 1, v1
	v_subrev_u32_e32 v232, s48, v42
	v_add_u32_e32 v232, v232, v36
	v_mov_b32_e32 v228, s48
	v_mov_b32_e32 v229, s49
	v_mov_b32_e32 v230, 0xee000000
	v_mov_b32_e32 v231, -1
	v_lshl_add_u64 v[228:229], v[228:229], 0, v[230:231]
	v_and_b32_e32 v116, 3, v176
	v_cmp_eq_u32_e32 vcc, 1, v116
	v_cndmask_b32_e32 v117, v0, v4, vcc
	v_cmp_eq_u32_e32 vcc, 2, v116
	v_cndmask_b32_e32 v117, v117, v2, vcc
	v_cmp_eq_u32_e32 vcc, 3, v116
	v_cndmask_b32_e32 v117, v117, v6, vcc
	v_lshlrev_b32_e32 v116, 1, v116
	v_sub_u32_e32 v118, v232, v116
	v_lshlrev_b32_e32 v220, v73, v117
	v_add_u32_e32 v220, v220, v46
	v_lshlrev_b32_e32 v220, 11, v220
	v_add_u32_e32 v220, v220, v118
	v_lshlrev_b32_e32 v220, 1, v220
	v_mov_b32_e32 v221, 0
	v_lshl_add_u64 v[220:221], v[220:221], 0, v[228:229]
	s_mov_b32 vcc_lo, 0x55555555
	s_mov_b32 vcc_hi, 0x55555555
	s_nop 1
	v_cndmask_b32_dpp v100, v13, v12, vcc quad_perm:[1,0,3,2] row_mask:0xf bank_mask:0xf
	v_cndmask_b32_dpp v102, v15, v14, vcc quad_perm:[1,0,3,2] row_mask:0xf bank_mask:0xf
	v_cndmask_b32_dpp v104, v17, v16, vcc quad_perm:[1,0,3,2] row_mask:0xf bank_mask:0xf
	v_cndmask_b32_dpp v106, v19, v18, vcc quad_perm:[1,0,3,2] row_mask:0xf bank_mask:0xf
	v_cndmask_b32_dpp v108, v29, v28, vcc quad_perm:[1,0,3,2] row_mask:0xf bank_mask:0xf
	v_cndmask_b32_dpp v110, v31, v30, vcc quad_perm:[1,0,3,2] row_mask:0xf bank_mask:0xf
	v_cndmask_b32_dpp v112, v21, v20, vcc quad_perm:[1,0,3,2] row_mask:0xf bank_mask:0xf
	v_cndmask_b32_dpp v114, v23, v22, vcc quad_perm:[1,0,3,2] row_mask:0xf bank_mask:0xf
	s_mov_b32 vcc_lo, 0xaaaaaaaa
	s_mov_b32 vcc_hi, 0xaaaaaaaa
	s_nop 1
	v_cndmask_b32_dpp v101, v12, v13, vcc quad_perm:[1,0,3,2] row_mask:0xf bank_mask:0xf
	v_cndmask_b32_dpp v103, v14, v15, vcc quad_perm:[1,0,3,2] row_mask:0xf bank_mask:0xf
	v_cndmask_b32_dpp v105, v16, v17, vcc quad_perm:[1,0,3,2] row_mask:0xf bank_mask:0xf
	v_cndmask_b32_dpp v107, v18, v19, vcc quad_perm:[1,0,3,2] row_mask:0xf bank_mask:0xf
	v_cndmask_b32_dpp v109, v28, v29, vcc quad_perm:[1,0,3,2] row_mask:0xf bank_mask:0xf
	v_cndmask_b32_dpp v111, v30, v31, vcc quad_perm:[1,0,3,2] row_mask:0xf bank_mask:0xf
	v_cndmask_b32_dpp v113, v20, v21, vcc quad_perm:[1,0,3,2] row_mask:0xf bank_mask:0xf
	v_cndmask_b32_dpp v115, v22, v23, vcc quad_perm:[1,0,3,2] row_mask:0xf bank_mask:0xf
	s_mov_b32 vcc_lo, 0x33333333
	s_mov_b32 vcc_hi, 0x33333333
	s_nop 1
	v_cndmask_b32_dpp v12, v102, v100, vcc quad_perm:[2,3,0,1] row_mask:0xf bank_mask:0xf
	v_cndmask_b32_dpp v13, v103, v101, vcc quad_perm:[2,3,0,1] row_mask:0xf bank_mask:0xf
	v_cndmask_b32_dpp v16, v106, v104, vcc quad_perm:[2,3,0,1] row_mask:0xf bank_mask:0xf
	v_cndmask_b32_dpp v17, v107, v105, vcc quad_perm:[2,3,0,1] row_mask:0xf bank_mask:0xf
	v_cndmask_b32_dpp v28, v110, v108, vcc quad_perm:[2,3,0,1] row_mask:0xf bank_mask:0xf
	v_cndmask_b32_dpp v29, v111, v109, vcc quad_perm:[2,3,0,1] row_mask:0xf bank_mask:0xf
	v_cndmask_b32_dpp v20, v114, v112, vcc quad_perm:[2,3,0,1] row_mask:0xf bank_mask:0xf
	v_cndmask_b32_dpp v21, v115, v113, vcc quad_perm:[2,3,0,1] row_mask:0xf bank_mask:0xf
	s_mov_b32 vcc_lo, 0xcccccccc
	s_mov_b32 vcc_hi, 0xcccccccc
	s_nop 1
	v_cndmask_b32_dpp v14, v100, v102, vcc quad_perm:[2,3,0,1] row_mask:0xf bank_mask:0xf
	v_cndmask_b32_dpp v15, v101, v103, vcc quad_perm:[2,3,0,1] row_mask:0xf bank_mask:0xf
	v_cndmask_b32_dpp v18, v104, v106, vcc quad_perm:[2,3,0,1] row_mask:0xf bank_mask:0xf
	v_cndmask_b32_dpp v19, v105, v107, vcc quad_perm:[2,3,0,1] row_mask:0xf bank_mask:0xf
	v_cndmask_b32_dpp v30, v108, v110, vcc quad_perm:[2,3,0,1] row_mask:0xf bank_mask:0xf
	v_cndmask_b32_dpp v31, v109, v111, vcc quad_perm:[2,3,0,1] row_mask:0xf bank_mask:0xf
	v_cndmask_b32_dpp v22, v112, v114, vcc quad_perm:[2,3,0,1] row_mask:0xf bank_mask:0xf
	v_cndmask_b32_dpp v23, v113, v115, vcc quad_perm:[2,3,0,1] row_mask:0xf bank_mask:0xf
	global_store_dwordx4 v[220:221], v[12:15], off
	global_store_dwordx4 v[220:221], v[16:19], off offset:64
	global_store_dwordx4 v[220:221], v[28:31], off offset:128
	global_store_dwordx4 v[220:221], v[20:23], off offset:192
	s_branch .LBB0_1986
